# lever 7: quad-row max/sum reductions via v_permlane16/32_swap instead of two dependent ds_bpermute round trips (attention max + l, GLA MODE-2 head-norm)
# speedup vs baseline: 1.0086x; 1.0029x over previous
.LBB0_689:
	ds_read_b128 v[102:105], v201 offset:6144
	ds_read_b128 v[106:109], v201 offset:6160
	s_waitcnt vmcnt(6)
	v_lshlrev_b32_e32 v138, 16, v98
	v_and_b32_e32 v139, 0xffff0000, v98
	s_waitcnt lgkmcnt(1)
	v_mul_f32_e32 v0, 0xbfb8aa3b, v102
	v_exp_f32_e32 v136, v0
	v_mul_f32_e32 v0, 0xbfb8aa3b, v103
	v_exp_f32_e32 v137, v0
	v_mul_f32_e32 v0, 0xbfb8aa3b, v104
	v_pk_mul_f32 v[136:137], v[136:137], v[138:139]
	s_nop 0
	v_cvt_pk_bf16_f32 v98, v136, v137
	v_exp_f32_e32 v136, v0
	v_mul_f32_e32 v0, 0xbfb8aa3b, v105
	v_exp_f32_e32 v137, v0
	v_lshlrev_b32_e32 v138, 16, v99
	v_and_b32_e32 v139, 0xffff0000, v99
	s_waitcnt lgkmcnt(0)
	v_mul_f32_e32 v0, 0xbfb8aa3b, v106
	v_pk_mul_f32 v[136:137], v[136:137], v[138:139]
	v_lshlrev_b32_e32 v138, 16, v100
	v_cvt_pk_bf16_f32 v99, v136, v137
	v_exp_f32_e32 v136, v0
	v_mul_f32_e32 v0, 0xbfb8aa3b, v107
	v_exp_f32_e32 v137, v0
	v_and_b32_e32 v139, 0xffff0000, v100
	v_mul_f32_e32 v0, 0xbfb8aa3b, v108
	v_pk_mul_f32 v[136:137], v[136:137], v[138:139]
	s_nop 0
	v_cvt_pk_bf16_f32 v100, v136, v137
	v_exp_f32_e32 v136, v0
	v_mul_f32_e32 v0, 0xbfb8aa3b, v109
	v_exp_f32_e32 v137, v0
	v_lshlrev_b32_e32 v138, 16, v101
	v_and_b32_e32 v139, 0xffff0000, v101
	v_mul_f32_e32 v0, 0x3fb8aa3b, v102
	v_pk_mul_f32 v[136:137], v[136:137], v[138:139]
	s_nop 0
	v_cvt_pk_bf16_f32 v101, v136, v137
	ds_write_b128 v181, v[98:101] offset:56320
	v_exp_f32_e32 v98, v0
	v_mul_f32_e32 v0, 0x3fb8aa3b, v103
	v_exp_f32_e32 v99, v0
	v_lshlrev_b32_e32 v100, 16, v94
	v_and_b32_e32 v101, 0xffff0000, v94
	v_mul_f32_e32 v0, 0x3fb8aa3b, v104
	v_pk_mul_f32 v[98:99], v[98:99], s[50:51] op_sel_hi:[1,0]
	s_waitcnt vmcnt(4)
	v_lshlrev_b32_e32 v104, 16, v90
	v_pk_mul_f32 v[98:99], v[98:99], v[100:101]
	v_lshlrev_b32_e32 v100, 16, v95
	v_cvt_pk_bf16_f32 v94, v98, v99
	v_exp_f32_e32 v98, v0
	v_mul_f32_e32 v0, 0x3fb8aa3b, v105
	v_exp_f32_e32 v99, v0
	v_and_b32_e32 v101, 0xffff0000, v95
	v_mul_f32_e32 v0, 0x3fb8aa3b, v106
	v_and_b32_e32 v105, 0xffff0000, v90
	v_pk_mul_f32 v[98:99], v[98:99], s[50:51] op_sel_hi:[1,0]
	s_nop 0
	v_pk_mul_f32 v[98:99], v[98:99], v[100:101]
	v_lshlrev_b32_e32 v100, 16, v96
	v_cvt_pk_bf16_f32 v95, v98, v99
	v_exp_f32_e32 v98, v0
	v_mul_f32_e32 v0, 0x3fb8aa3b, v107
	v_exp_f32_e32 v99, v0
	v_and_b32_e32 v101, 0xffff0000, v96
	v_mul_f32_e32 v0, 0x3fb8aa3b, v108
	v_pk_mul_f32 v[98:99], v[98:99], s[50:51] op_sel_hi:[1,0]
	s_nop 0
	v_pk_mul_f32 v[98:99], v[98:99], v[100:101]
	v_lshlrev_b32_e32 v100, 16, v97
	v_cvt_pk_bf16_f32 v96, v98, v99
	v_exp_f32_e32 v98, v0
	v_mul_f32_e32 v0, 0x3fb8aa3b, v109
	v_exp_f32_e32 v99, v0
	v_and_b32_e32 v101, 0xffff0000, v97
	v_pk_mul_f32 v[98:99], v[98:99], s[50:51] op_sel_hi:[1,0]
	s_nop 0
	v_pk_mul_f32 v[98:99], v[98:99], v[100:101]
	s_nop 0
	v_cvt_pk_bf16_f32 v97, v98, v99
	ds_write_b128 v181, v[94:97] offset:38912
	ds_read_b128 v[94:97], v202 offset:6144
	ds_read_b128 v[98:101], v202 offset:6160
	s_waitcnt lgkmcnt(1)
	v_mul_f32_e32 v0, 0xbfb8aa3b, v94
	v_exp_f32_e32 v102, v0
	v_mul_f32_e32 v0, 0xbfb8aa3b, v95
	v_exp_f32_e32 v103, v0
	v_mul_f32_e32 v0, 0xbfb8aa3b, v96
	v_pk_mul_f32 v[102:103], v[102:103], v[104:105]
	s_nop 0
	v_cvt_pk_bf16_f32 v90, v102, v103
	v_exp_f32_e32 v102, v0
	v_mul_f32_e32 v0, 0xbfb8aa3b, v97
	v_exp_f32_e32 v103, v0
	v_lshlrev_b32_e32 v104, 16, v91
	v_and_b32_e32 v105, 0xffff0000, v91
	s_waitcnt lgkmcnt(0)
	v_mul_f32_e32 v0, 0xbfb8aa3b, v98
	v_pk_mul_f32 v[102:103], v[102:103], v[104:105]
	v_lshlrev_b32_e32 v104, 16, v92
	v_cvt_pk_bf16_f32 v91, v102, v103
	v_exp_f32_e32 v102, v0
	v_mul_f32_e32 v0, 0xbfb8aa3b, v99
	v_exp_f32_e32 v103, v0
	v_and_b32_e32 v105, 0xffff0000, v92
	v_mul_f32_e32 v0, 0xbfb8aa3b, v100
	v_pk_mul_f32 v[102:103], v[102:103], v[104:105]
	s_nop 0
	v_cvt_pk_bf16_f32 v92, v102, v103
	v_exp_f32_e32 v102, v0
	v_mul_f32_e32 v0, 0xbfb8aa3b, v101
	v_exp_f32_e32 v103, v0
	v_lshlrev_b32_e32 v104, 16, v93
	v_and_b32_e32 v105, 0xffff0000, v93
	v_mul_f32_e32 v0, 0x3fb8aa3b, v94
	v_pk_mul_f32 v[102:103], v[102:103], v[104:105]
	s_nop 0
	v_cvt_pk_bf16_f32 v93, v102, v103
	ds_write_b128 v182, v[90:93] offset:56320
	v_exp_f32_e32 v90, v0
	v_mul_f32_e32 v0, 0x3fb8aa3b, v95
	v_exp_f32_e32 v91, v0
	v_lshlrev_b32_e32 v92, 16, v70
	v_and_b32_e32 v93, 0xffff0000, v70
	v_mul_f32_e32 v0, 0x3fb8aa3b, v96
	v_pk_mul_f32 v[90:91], v[90:91], s[50:51] op_sel_hi:[1,0]
	s_nop 0
	v_pk_mul_f32 v[90:91], v[90:91], v[92:93]
	v_lshlrev_b32_e32 v92, 16, v71
	v_cvt_pk_bf16_f32 v70, v90, v91
	v_exp_f32_e32 v90, v0
	v_mul_f32_e32 v0, 0x3fb8aa3b, v97
	v_exp_f32_e32 v91, v0
	v_and_b32_e32 v93, 0xffff0000, v71
	v_mul_f32_e32 v0, 0x3fb8aa3b, v98
	v_pk_mul_f32 v[90:91], v[90:91], s[50:51] op_sel_hi:[1,0]
	s_nop 0
	v_pk_mul_f32 v[90:91], v[90:91], v[92:93]
	v_lshlrev_b32_e32 v92, 16, v72
	v_cvt_pk_bf16_f32 v71, v90, v91
	v_exp_f32_e32 v90, v0
	v_mul_f32_e32 v0, 0x3fb8aa3b, v99
	v_exp_f32_e32 v91, v0
	v_and_b32_e32 v93, 0xffff0000, v72
	v_mul_f32_e32 v0, 0x3fb8aa3b, v100
	v_pk_mul_f32 v[90:91], v[90:91], s[50:51] op_sel_hi:[1,0]
	s_nop 0
	v_pk_mul_f32 v[90:91], v[90:91], v[92:93]
	v_lshlrev_b32_e32 v92, 16, v73
	v_cvt_pk_bf16_f32 v72, v90, v91
	v_exp_f32_e32 v90, v0
	v_mul_f32_e32 v0, 0x3fb8aa3b, v101
	v_exp_f32_e32 v91, v0
	v_and_b32_e32 v93, 0xffff0000, v73
	v_pk_mul_f32 v[90:91], v[90:91], s[50:51] op_sel_hi:[1,0]
	s_nop 0
	v_pk_mul_f32 v[90:91], v[90:91], v[92:93]
	s_nop 0
	v_cvt_pk_bf16_f32 v73, v90, v91
	ds_write_b128 v182, v[70:73] offset:38912
	s_waitcnt vmcnt(3)
	ds_write_b128 v203, v[74:77]
	s_waitcnt vmcnt(2)
	ds_write_b128 v204, v[78:81]
	s_waitcnt vmcnt(1)
	ds_write_b128 v203, v[82:85] offset:16896
	s_waitcnt vmcnt(0)
	ds_write_b128 v205, v[86:89]
	v_lshl_add_u64 v[70:71], s[58:59], 0, v[116:117]
	v_lshl_add_u64 v[72:73], s[58:59], 0, v[120:121]
	v_lshl_add_u64 v[74:75], s[58:59], 0, v[122:123]
	global_load_dwordx2 v[156:157], v[70:71], off
	global_load_dwordx2 v[152:153], v[70:71], off offset:32
	global_load_dwordx2 v[148:149], v[72:73], off
	global_load_dwordx2 v[146:147], v[74:75], off
	v_lshl_add_u64 v[70:71], s[58:59], 0, v[124:125]
	v_lshl_add_u64 v[72:73], s[58:59], 0, v[126:127]
	v_lshl_add_u64 v[74:75], s[58:59], 0, v[128:129]
	v_lshl_add_u64 v[76:77], s[58:59], 0, v[130:131]
	global_load_dwordx2 v[144:145], v[70:71], off
	global_load_dwordx2 v[142:143], v[72:73], off
	global_load_dwordx2 v[138:139], v[74:75], off
	global_load_dwordx2 v[136:137], v[76:77], off
	s_waitcnt lgkmcnt(0)
	s_barrier
	ds_read_b128 v[70:73], v206 offset:56320
	ds_read_b128 v[74:77], v180 offset:38912
	ds_read_b128 v[78:81], v206 offset:56384
	ds_read_b128 v[82:85], v180 offset:38976
	s_waitcnt lgkmcnt(2)
	v_mfma_f32_16x16x32_bf16 v[70:73], v[70:73], v[74:77], 0
	v_mov_b32_e32 v0, s49
	v_cvt_pk_bf16_f32 v166, v62, v63
	v_cvt_pk_bf16_f32 v167, v64, v65
	s_waitcnt lgkmcnt(0)
	v_mfma_f32_16x16x32_bf16 v[70:73], v[78:81], v[82:85], v[70:73]
	ds_read_b128 v[78:81], v206 offset:56448
	ds_read_b128 v[86:89], v180 offset:39040
	v_cvt_pk_bf16_f32 v168, v66, v67
	v_cvt_pk_bf16_f32 v169, v68, v69
	s_waitcnt lgkmcnt(0)
	v_mfma_f32_16x16x32_bf16 v[70:73], v[78:81], v[86:89], v[70:73]
	ds_read_b128 v[78:81], v206 offset:56512
	ds_read_b128 v[90:93], v180 offset:39104
	s_add_u32 s55, s72, s68
	s_addc_u32 s63, s73, 0
	s_waitcnt lgkmcnt(0)
	v_mfma_f32_16x16x32_bf16 v[70:73], v[78:81], v[90:93], v[70:73]
	s_add_u32 s62, s55, 0xafc1000
	s_addc_u32 s63, s63, 0
	s_waitcnt vmcnt(7)
	v_lshlrev_b32_e32 v224, 16, v156
	s_nop 3
	v_cndmask_b32_e64 v0, v70, v0, s[14:15]
	v_cndmask_b32_e64 v70, v71, 0, s[30:31]
	v_cndmask_b32_e64 v71, v72, 0, s[34:35]
	v_cndmask_b32_e64 v72, v73, 0, s[36:37]
	v_cvt_pk_bf16_f32 v70, v0, v70
	v_cvt_pk_bf16_f32 v71, v71, v72
	ds_write_b64 v207, v[70:71]
	ds_read_b128 v[70:73], v208 offset:56320
	s_waitcnt lgkmcnt(0)
	v_mfma_f32_16x16x32_bf16 v[70:73], v[70:73], v[74:77], 0
	ds_read_b128 v[74:77], v208 offset:56384
	v_mov_b32_e32 v0, s49
	v_and_b32_e32 v225, 0xffff0000, v156
	s_waitcnt lgkmcnt(0)
	v_mfma_f32_16x16x32_bf16 v[70:73], v[74:77], v[82:85], v[70:73]
	ds_read_b128 v[74:77], v208 offset:56448
	v_lshlrev_b32_e32 v156, 16, v157
	v_and_b32_e32 v157, 0xffff0000, v157
	s_waitcnt lgkmcnt(0)
	v_mfma_f32_16x16x32_bf16 v[70:73], v[74:77], v[86:89], v[70:73]
	ds_read_b128 v[74:77], v208 offset:56512
	s_waitcnt vmcnt(6)
	v_lshlrev_b32_e32 v226, 16, v152
	v_and_b32_e32 v227, 0xffff0000, v152
	s_waitcnt lgkmcnt(0)
	v_mfma_f32_16x16x32_bf16 v[70:73], v[74:77], v[90:93], v[70:73]
	v_lshlrev_b32_e32 v152, 16, v153
	v_and_b32_e32 v153, 0xffff0000, v153
	s_nop 5
	v_cndmask_b32_e64 v0, v70, v0, s[22:23]
	v_cndmask_b32_e64 v70, v71, 0, s[38:39]
	v_cndmask_b32_e64 v71, v72, 0, s[40:41]
	v_cndmask_b32_e64 v72, v73, 0, s[42:43]
	v_cvt_pk_bf16_f32 v70, v0, v70
	v_cvt_pk_bf16_f32 v71, v71, v72
	ds_write_b64 v209, v[70:71]
	s_waitcnt lgkmcnt(0)
	s_barrier
	ds_read_b64_tr_b16 v[72:73], v210 offset:2112
	ds_read_b64_tr_b16 v[70:71], v210
	ds_read_b64_tr_b16 v[74:75], v210 offset:32
	ds_read_b64_tr_b16 v[78:79], v210 offset:16896
	ds_read_b64_tr_b16 v[80:81], v210 offset:19008
	ds_read_b64_tr_b16 v[76:77], v210 offset:2144
	ds_read_b64_tr_b16 v[82:83], v210 offset:16928
	ds_read_b64_tr_b16 v[84:85], v210 offset:19040
	ds_read_b128 v[86:89], v211
	ds_read_b128 v[94:97], v211 offset:64
	ds_read_b128 v[102:105], v211 offset:2368
	s_waitcnt lgkmcnt(2)
	v_mfma_f32_16x16x32_bf16 v[90:93], v[70:73], v[86:89], 0
	ds_read_b128 v[158:161], v211 offset:4672
	v_mfma_f32_16x16x32_bf16 v[86:89], v[74:77], v[86:89], 0
	s_waitcnt lgkmcnt(2)
	v_mfma_f32_16x16x32_bf16 v[90:93], v[78:81], v[94:97], v[90:93]
	v_mfma_f32_16x16x32_bf16 v[86:89], v[82:85], v[94:97], v[86:89]
	ds_read_b128 v[94:97], v211 offset:2304
	s_waitcnt lgkmcnt(0)
	v_mfma_f32_16x16x32_bf16 v[98:101], v[70:73], v[94:97], 0
	v_mfma_f32_16x16x32_bf16 v[94:97], v[74:77], v[94:97], 0
	v_mfma_f32_16x16x32_bf16 v[98:101], v[78:81], v[102:105], v[98:101]
	v_mfma_f32_16x16x32_bf16 v[94:97], v[82:85], v[102:105], v[94:97]
	ds_read_b128 v[102:105], v211 offset:4608
	s_waitcnt lgkmcnt(0)
	v_mfma_f32_16x16x32_bf16 v[106:109], v[70:73], v[102:105], 0
	v_mfma_f32_16x16x32_bf16 v[102:105], v[74:77], v[102:105], 0
	v_mfma_f32_16x16x32_bf16 v[106:109], v[78:81], v[158:161], v[106:109]
	v_mfma_f32_16x16x32_bf16 v[102:105], v[82:85], v[158:161], v[102:105]
	ds_read_b128 v[158:161], v211 offset:6912
	s_waitcnt lgkmcnt(0)
	v_mfma_f32_16x16x32_bf16 v[70:73], v[70:73], v[158:161], 0
	v_mfma_f32_16x16x32_bf16 v[74:77], v[74:77], v[158:161], 0
	ds_read_b128 v[158:161], v211 offset:6976
	s_waitcnt lgkmcnt(0)
	v_mfma_f32_16x16x32_bf16 v[70:73], v[78:81], v[158:161], v[70:73]
	v_cvt_pk_bf16_f32 v78, v30, v31
	v_cvt_pk_bf16_f32 v79, v32, v33
	v_cvt_pk_bf16_f32 v80, v10, v11
	v_mfma_f32_16x16x32_bf16 v[74:77], v[82:85], v[158:161], v[74:77]
	v_cvt_pk_bf16_f32 v81, v12, v13
	v_cvt_pk_bf16_f32 v82, v6, v7
	v_cvt_pk_bf16_f32 v83, v8, v9
	v_cvt_pk_bf16_f32 v84, v18, v19
	v_cvt_pk_bf16_f32 v85, v20, v21
	ds_read2_b64 v[158:161], v215 offset1:4
	s_waitcnt lgkmcnt(0)
	v_mfma_f32_16x16x32_bf16 v[90:93], v[78:81], v[158:161], v[90:93]
	v_mfma_f32_16x16x32_bf16 v[86:89], v[82:85], v[158:161], v[86:89]
	ds_read2_b64 v[158:161], v216 offset0:32 offset1:36
	s_waitcnt lgkmcnt(0)
	v_mfma_f32_16x16x32_bf16 v[98:101], v[78:81], v[158:161], v[98:101]
	v_mfma_f32_16x16x32_bf16 v[94:97], v[82:85], v[158:161], v[94:97]
	ds_read2_b64 v[158:161], v217 offset0:64 offset1:68
	s_waitcnt lgkmcnt(0)
	v_mfma_f32_16x16x32_bf16 v[106:109], v[78:81], v[158:161], v[106:109]
	v_mfma_f32_16x16x32_bf16 v[102:105], v[82:85], v[158:161], v[102:105]
	ds_read2_b64 v[158:161], v218 offset0:96 offset1:100
	s_waitcnt lgkmcnt(0)
	v_mfma_f32_16x16x32_bf16 v[70:73], v[78:81], v[158:161], v[70:73]
	v_cvt_pk_bf16_f32 v78, v14, v15
	v_cvt_pk_bf16_f32 v79, v16, v17
	v_cvt_pk_bf16_f32 v80, v38, v39
	v_mfma_f32_16x16x32_bf16 v[74:77], v[82:85], v[158:161], v[74:77]
	v_cvt_pk_bf16_f32 v81, v40, v41
	v_cvt_pk_bf16_f32 v82, v26, v27
	v_cvt_pk_bf16_f32 v83, v28, v29
	v_cvt_pk_bf16_f32 v84, v50, v51
	v_cvt_pk_bf16_f32 v85, v52, v53
	ds_read2_b64 v[158:161], v215 offset0:8 offset1:12
	s_waitcnt lgkmcnt(0)
	v_mfma_f32_16x16x32_bf16 v[90:93], v[78:81], v[158:161], v[90:93]
	v_mfma_f32_16x16x32_bf16 v[86:89], v[82:85], v[158:161], v[86:89]
	ds_read2_b64 v[158:161], v216 offset0:40 offset1:44
	s_waitcnt lgkmcnt(0)
	v_mfma_f32_16x16x32_bf16 v[98:101], v[78:81], v[158:161], v[98:101]
	v_mfma_f32_16x16x32_bf16 v[94:97], v[82:85], v[158:161], v[94:97]
	ds_read2_b64 v[158:161], v217 offset0:72 offset1:76
	s_waitcnt lgkmcnt(0)
	v_mfma_f32_16x16x32_bf16 v[106:109], v[78:81], v[158:161], v[106:109]
	v_mfma_f32_16x16x32_bf16 v[102:105], v[82:85], v[158:161], v[102:105]
	ds_read2_b64 v[158:161], v218 offset0:104 offset1:108
	s_waitcnt lgkmcnt(0)
	v_mfma_f32_16x16x32_bf16 v[70:73], v[78:81], v[158:161], v[70:73]
	v_cvt_pk_bf16_f32 v78, v22, v23
	v_cvt_pk_bf16_f32 v79, v24, v25
	v_cvt_pk_bf16_f32 v80, v42, v43
	v_mfma_f32_16x16x32_bf16 v[74:77], v[82:85], v[158:161], v[74:77]
	v_cvt_pk_bf16_f32 v81, v44, v45
	v_cvt_pk_bf16_f32 v82, v34, v35
	v_cvt_pk_bf16_f32 v83, v36, v37
	v_cvt_pk_bf16_f32 v84, v54, v55
	v_cvt_pk_bf16_f32 v85, v56, v57
	ds_read2_b64 v[158:161], v215 offset0:16 offset1:20
	s_waitcnt lgkmcnt(0)
	v_mfma_f32_16x16x32_bf16 v[90:93], v[78:81], v[158:161], v[90:93]
	v_mfma_f32_16x16x32_bf16 v[86:89], v[82:85], v[158:161], v[86:89]
	ds_read2_b64 v[158:161], v216 offset0:48 offset1:52
	s_waitcnt lgkmcnt(0)
	v_mfma_f32_16x16x32_bf16 v[98:101], v[78:81], v[158:161], v[98:101]
	v_mfma_f32_16x16x32_bf16 v[94:97], v[82:85], v[158:161], v[94:97]
	ds_read2_b64 v[158:161], v217 offset0:80 offset1:84
	s_waitcnt lgkmcnt(0)
	v_mfma_f32_16x16x32_bf16 v[162:165], v[78:81], v[158:161], v[106:109]
	v_mfma_f32_16x16x32_bf16 v[158:161], v[82:85], v[158:161], v[102:105]
	s_nop 2
	ds_read2_b64 v[102:105], v218 offset0:112 offset1:116
	s_waitcnt lgkmcnt(0)
	v_mfma_f32_16x16x32_bf16 v[70:73], v[78:81], v[102:105], v[70:73]
	v_cvt_pk_bf16_f32 v78, v46, v47
	v_cvt_pk_bf16_f32 v79, v48, v49
	v_cvt_pk_bf16_f32 v80, v58, v59
	v_mfma_f32_16x16x32_bf16 v[74:77], v[82:85], v[102:105], v[74:77]
	v_cvt_pk_bf16_f32 v81, v60, v61
	ds_read2_b64 v[82:85], v215 offset0:24 offset1:28
	s_waitcnt lgkmcnt(0)
	v_mfma_f32_16x16x32_bf16 v[106:109], v[78:81], v[82:85], v[90:93]
	v_mfma_f32_16x16x32_bf16 v[102:105], v[166:169], v[82:85], v[86:89]
	ds_read2_b64 v[82:85], v216 offset0:56 offset1:60
	s_nop 5
	v_pk_add_f32 v[106:107], v[106:107], v[224:225]
	v_pk_add_f32 v[108:109], v[108:109], v[156:157]
	s_waitcnt lgkmcnt(0)
	v_mfma_f32_16x16x32_bf16 v[98:101], v[78:81], v[82:85], v[98:101]
	v_mul_f32_e64 v156, v106, v106
	v_mul_f32_e64 v157, v107, v107
	v_pk_mul_f32 v[224:225], v[108:109], v[108:109]
	v_add_f32_e32 v0, v156, v157
	v_mfma_f32_16x16x32_bf16 v[94:97], v[166:169], v[82:85], v[94:97]
	ds_read2_b64 v[82:85], v217 offset0:88 offset1:92
	v_pk_add_f32 v[102:103], v[102:103], v[226:227]
	v_add_f32_e32 v0, v224, v0
	s_waitcnt lgkmcnt(0)
	v_mfma_f32_16x16x32_bf16 v[86:89], v[166:169], v[82:85], v[158:161]
	v_add_f32_e64 v104, v104, v152
	v_add_f32_e64 v105, v105, v153
	s_nop 0
	ds_read2_b64 v[158:161], v218 offset0:120 offset1:124
	v_pk_mul_f32 v[152:153], v[102:103], v[102:103]
	v_mfma_f32_16x16x32_bf16 v[90:93], v[78:81], v[82:85], v[162:165]
	v_add_f32_e32 v0, v225, v0
	v_add_f32_e32 v0, v152, v0
	v_pk_mul_f32 v[226:227], v[104:105], v[104:105]
	s_waitcnt lgkmcnt(0)
	v_mfma_f32_16x16x32_bf16 v[82:85], v[78:81], v[158:161], v[70:73]
	v_add_f32_e32 v0, v153, v0
	v_add_f32_e32 v0, v226, v0
	v_add_f32_e32 v0, v227, v0
	v_lshl_add_u64 v[70:71], s[62:63], 0, v[118:119]
	v_add_co_u32_e32 v72, vcc, s81, v70
	v_mfma_f32_16x16x32_bf16 v[78:81], v[166:169], v[158:161], v[74:77]
	s_nop 0
	v_addc_co_u32_e32 v73, vcc, 0, v71, vcc
	global_load_dwordx2 v[168:169], v[70:71], off
	global_load_dwordx2 v[166:167], v[70:71], off offset:32
	global_load_dwordx2 v[164:165], v[72:73], off
	global_load_dwordx2 v[162:163], v[72:73], off offset:32
	v_add_co_u32_e32 v72, vcc, s95, v70
	v_mov_b32_e32 v152, v0
	s_nop 1
	v_permlane16_swap_b32_e32 v152, v0
	s_nop 0
	v_addc_co_u32_e32 v73, vcc, 0, v71, vcc
	v_add_co_u32_e32 v70, vcc, s96, v70
	global_load_dwordx2 v[160:161], v[72:73], off
	global_load_dwordx2 v[158:159], v[72:73], off offset:32
	v_addc_co_u32_e32 v71, vcc, 0, v71, vcc
	global_load_dwordx2 v[150:151], v[70:71], off
	global_load_dwordx2 v[140:141], v[70:71], off offset:32
	global_load_dwordx4 v[74:77], v[134:135], off
	s_nop 0
	global_load_dwordx4 v[70:73], v[134:135], off offset:64
	s_waitcnt lgkmcnt(0)
	v_add_f32_e32 v0, v0, v152
	v_mov_b32_e32 v152, v0
	s_nop 1
	v_permlane32_swap_b32_e32 v152, v0
	s_and_saveexec_b64 s[62:63], s[4:5]
	s_cbranch_execz .LBB0_691
	s_waitcnt lgkmcnt(0)
	v_add_f32_e32 v0, v0, v152
	ds_write_b32 v185, v0
.LBB0_691:
	s_or_b64 exec, exec, s[62:63]
	s_waitcnt vmcnt(15) lgkmcnt(0)
	v_lshlrev_b32_e32 v152, 16, v148
	v_and_b32_e32 v153, 0xffff0000, v148
	v_pk_add_f32 v[152:153], v[98:99], v[152:153]
	v_lshlrev_b32_e32 v98, 16, v149
	v_and_b32_e32 v99, 0xffff0000, v149
	v_pk_add_f32 v[100:101], v[100:101], v[98:99]
	v_pk_mul_f32 v[148:149], v[152:153], v[152:153]
	v_pk_mul_f32 v[156:157], v[100:101], v[100:101]
	s_waitcnt vmcnt(14)
	v_lshlrev_b32_e32 v98, 16, v146
	v_and_b32_e32 v99, 0xffff0000, v146
	v_add_f32_e32 v0, v148, v149
	v_pk_add_f32 v[98:99], v[94:95], v[98:99]
	v_lshlrev_b32_e32 v94, 16, v147
	v_and_b32_e32 v95, 0xffff0000, v147
	v_add_f32_e32 v0, v156, v0
	v_pk_add_f32 v[96:97], v[96:97], v[94:95]
	v_pk_mul_f32 v[94:95], v[98:99], v[98:99]
	v_add_f32_e32 v0, v157, v0
	v_add_f32_e32 v0, v94, v0
	v_pk_mul_f32 v[146:147], v[96:97], v[96:97]
	v_add_f32_e32 v0, v95, v0
	v_add_f32_e32 v0, v146, v0
	v_add_f32_e32 v0, v147, v0
	v_mov_b32_e32 v94, v0
	s_nop 1
	v_permlane16_swap_b32_e32 v94, v0
	s_waitcnt lgkmcnt(0)
	v_add_f32_e32 v0, v0, v94
	v_mov_b32_e32 v94, v0
	s_nop 1
	v_permlane32_swap_b32_e32 v94, v0
	s_and_saveexec_b64 s[62:63], s[4:5]
	s_cbranch_execz .LBB0_693
	s_waitcnt lgkmcnt(0)
	v_add_f32_e32 v0, v0, v94
	ds_write_b32 v185, v0 offset:512
.LBB0_693:
	s_or_b64 exec, exec, s[62:63]
	s_waitcnt vmcnt(13) lgkmcnt(0)
	v_lshlrev_b32_e32 v94, 16, v144
	v_and_b32_e32 v95, 0xffff0000, v144
	v_pk_add_f32 v[90:91], v[90:91], v[94:95]
	v_lshlrev_b32_e32 v94, 16, v145
	v_and_b32_e32 v95, 0xffff0000, v145
	v_pk_add_f32 v[94:95], v[92:93], v[94:95]
	v_pk_mul_f32 v[144:145], v[90:91], v[90:91]
	v_pk_mul_f32 v[146:147], v[94:95], v[94:95]
	s_waitcnt vmcnt(12)
	v_lshlrev_b32_e32 v92, 16, v142
	v_and_b32_e32 v93, 0xffff0000, v142
	v_add_f32_e32 v0, v144, v145
	v_pk_add_f32 v[92:93], v[86:87], v[92:93]
	v_lshlrev_b32_e32 v86, 16, v143
	v_and_b32_e32 v87, 0xffff0000, v143
	v_add_f32_e32 v0, v146, v0
	v_pk_add_f32 v[88:89], v[88:89], v[86:87]
	v_pk_mul_f32 v[86:87], v[92:93], v[92:93]
	v_add_f32_e32 v0, v147, v0
	v_add_f32_e32 v0, v86, v0
	v_pk_mul_f32 v[142:143], v[88:89], v[88:89]
	v_add_f32_e32 v0, v87, v0
	v_add_f32_e32 v0, v142, v0
	v_add_f32_e32 v0, v143, v0
	v_mov_b32_e32 v86, v0
	s_nop 1
	v_permlane16_swap_b32_e32 v86, v0
	s_waitcnt lgkmcnt(0)
	v_add_f32_e32 v0, v0, v86
	v_mov_b32_e32 v86, v0
	s_nop 1
	v_permlane32_swap_b32_e32 v86, v0
	s_and_saveexec_b64 s[62:63], s[4:5]
	s_cbranch_execz .LBB0_695
	s_waitcnt lgkmcnt(0)
	v_add_f32_e32 v0, v0, v86
	ds_write_b32 v185, v0 offset:1024
.LBB0_695:
	s_or_b64 exec, exec, s[62:63]
	s_waitcnt vmcnt(11) lgkmcnt(0)
	v_lshlrev_b32_e32 v86, 16, v138
	v_and_b32_e32 v87, 0xffff0000, v138
	v_pk_add_f32 v[86:87], v[82:83], v[86:87]
	v_lshlrev_b32_e32 v82, 16, v139
	v_and_b32_e32 v83, 0xffff0000, v139
	v_pk_add_f32 v[84:85], v[84:85], v[82:83]
	v_pk_mul_f32 v[138:139], v[86:87], v[86:87]
	v_pk_mul_f32 v[142:143], v[84:85], v[84:85]
	s_waitcnt vmcnt(10)
	v_lshlrev_b32_e32 v82, 16, v136
	v_and_b32_e32 v83, 0xffff0000, v136
	v_add_f32_e32 v0, v138, v139
	v_pk_add_f32 v[82:83], v[78:79], v[82:83]
	v_lshlrev_b32_e32 v78, 16, v137
	v_and_b32_e32 v79, 0xffff0000, v137
	v_add_f32_e32 v0, v142, v0
	v_pk_add_f32 v[78:79], v[80:81], v[78:79]
	v_pk_mul_f32 v[80:81], v[82:83], v[82:83]
	v_add_f32_e32 v0, v143, v0
	v_add_f32_e32 v0, v80, v0
	v_pk_mul_f32 v[136:137], v[78:79], v[78:79]
	v_add_f32_e32 v0, v81, v0
	v_add_f32_e32 v0, v136, v0
	v_add_f32_e32 v0, v137, v0
	v_mov_b32_e32 v80, v0
	s_nop 1
	v_permlane16_swap_b32_e32 v80, v0
	s_waitcnt lgkmcnt(0)
	v_add_f32_e32 v0, v0, v80
	v_mov_b32_e32 v80, v0
	s_nop 1
	v_permlane32_swap_b32_e32 v80, v0
	s_and_saveexec_b64 s[62:63], s[4:5]
	s_cbranch_execz .LBB0_679
	s_waitcnt lgkmcnt(0)
	v_add_f32_e32 v0, v0, v80
	ds_write_b32 v185, v0 offset:1536
	s_branch .LBB0_679

.LBB0_1036:
	s_waitcnt vmcnt(0)
	v_mov_b32_e32 v6, v149
	v_mov_b32_e32 v10, v149
	s_nop 1
	v_permlane16_swap_b32_e32 v6, v10
	v_lshlrev_b64 v[0:1], 11, v[156:157]
	v_lshl_add_u64 v[0:1], s[84:85], 0, v[0:1]
	s_lshl_b32 s80, s89, 7
	v_lshlrev_b32_e32 v72, 1, v78
	s_waitcnt lgkmcnt(0)
	v_add_f32_e32 v10, v10, v6
	v_mov_b32_e32 v11, v10
	s_nop 1
	v_permlane32_swap_b32_e32 v11, v10
	v_lshl_add_u64 v[6:7], v[0:1], 0, s[80:81]
	v_lshl_add_u64 v[8:9], v[6:7], 0, v[72:73]
	s_waitcnt lgkmcnt(0)
	v_add_f32_e32 v0, v10, v11
	v_div_scale_f32 v1, s[0:1], v0, v0, 1.0
	v_div_scale_f32 v13, vcc, 1.0, v0, 1.0
	v_rcp_f32_e32 v12, v1
	s_nop 1
	v_fma_f32 v14, -v1, v12, 1.0
	v_fmac_f32_e32 v12, v14, v12
	v_mul_f32_e32 v14, v13, v12
	v_fma_f32 v15, -v1, v14, v13
	v_fmac_f32_e32 v14, v15, v12
	v_fma_f32 v1, -v1, v14, v13
	v_div_fmas_f32 v1, v1, v12, v14
	v_div_fixup_f32 v0, v1, v0, 1.0
	v_readlane_b32 s0, v240, 11
	s_add_i32 s73, s73, s0
	s_cmpk_lt_i32 s73, 0x1080
	v_readlane_b32 s1, v240, 12
	v_lshlrev_b32_e32 v12, 16, v242
	v_and_b32_e32 v13, 0xffff0000, v242
	v_lshlrev_b32_e32 v4, 16, v243
	v_and_b32_e32 v5, 0xffff0000, v243
	v_mul_f32_e32 v1, 0xbfb8aa3b, v12
	v_mul_f32_e32 v14, 0xbfb8aa3b, v13
	v_mul_f32_e32 v15, 0xbfb8aa3b, v4
	v_mul_f32_e32 v16, 0xbfb8aa3b, v5
	v_exp_f32_e32 v1, v1
	v_exp_f32_e32 v14, v14
	v_exp_f32_e32 v15, v15
	v_exp_f32_e32 v16, v16
	v_add_f32_e32 v1, 1.0, v1
	v_add_f32_e32 v17, 1.0, v14
	v_add_f32_e32 v18, 1.0, v15
	v_add_f32_e32 v19, 1.0, v16
	v_rcp_f32_e32 v14, v1
	v_rcp_f32_e32 v15, v17
	v_rcp_f32_e32 v16, v18
	v_rcp_f32_e32 v17, v19
	v_pk_mul_f32 v[18:19], v[36:37], v[0:1] op_sel_hi:[1,0]
	v_pk_mul_f32 v[20:21], v[38:39], v[0:1] op_sel_hi:[1,0]
	v_pk_mul_f32 v[12:13], v[14:15], v[12:13]
	v_pk_mul_f32 v[4:5], v[16:17], v[4:5]
	v_pk_mul_f32 v[12:13], v[18:19], v[12:13]
	v_pk_mul_f32 v[4:5], v[20:21], v[4:5]
	v_cvt_pk_bf16_f32 v12, v12, v13
	v_cvt_pk_bf16_f32 v13, v4, v5
	global_store_dwordx2 v[8:9], v[12:13], off
	v_lshlrev_b32_e32 v12, 16, v244
	v_and_b32_e32 v13, 0xffff0000, v244
	v_lshlrev_b32_e32 v4, 16, v245
	v_and_b32_e32 v5, 0xffff0000, v245
	v_mul_f32_e32 v1, 0xbfb8aa3b, v12
	v_mul_f32_e32 v14, 0xbfb8aa3b, v13
	v_mul_f32_e32 v15, 0xbfb8aa3b, v4
	v_mul_f32_e32 v16, 0xbfb8aa3b, v5
	v_exp_f32_e32 v1, v1
	v_exp_f32_e32 v14, v14
	v_exp_f32_e32 v15, v15
	v_exp_f32_e32 v16, v16
	v_add_f32_e32 v1, 1.0, v1
	v_add_f32_e32 v17, 1.0, v14
	v_add_f32_e32 v18, 1.0, v15
	v_add_f32_e32 v19, 1.0, v16
	v_rcp_f32_e32 v14, v1
	v_rcp_f32_e32 v15, v17
	v_rcp_f32_e32 v16, v18
	v_rcp_f32_e32 v17, v19
	v_pk_mul_f32 v[18:19], v[32:33], v[0:1] op_sel_hi:[1,0]
	v_pk_mul_f32 v[20:21], v[34:35], v[0:1] op_sel_hi:[1,0]
	v_pk_mul_f32 v[12:13], v[14:15], v[12:13]
	v_pk_mul_f32 v[4:5], v[16:17], v[4:5]
	v_pk_mul_f32 v[12:13], v[18:19], v[12:13]
	v_pk_mul_f32 v[4:5], v[20:21], v[4:5]
	v_cvt_pk_bf16_f32 v12, v12, v13
	v_cvt_pk_bf16_f32 v13, v4, v5
	global_store_dwordx2 v[8:9], v[12:13], off offset:32
	v_lshlrev_b32_e32 v12, 16, v246
	v_and_b32_e32 v13, 0xffff0000, v246
	v_lshlrev_b32_e32 v4, 16, v247
	v_and_b32_e32 v5, 0xffff0000, v247
	v_mul_f32_e32 v1, 0xbfb8aa3b, v12
	v_mul_f32_e32 v14, 0xbfb8aa3b, v13
	v_mul_f32_e32 v15, 0xbfb8aa3b, v4
	v_mul_f32_e32 v16, 0xbfb8aa3b, v5
	v_exp_f32_e32 v1, v1
	v_exp_f32_e32 v14, v14
	v_exp_f32_e32 v15, v15
	v_exp_f32_e32 v16, v16
	v_add_f32_e32 v1, 1.0, v1
	v_add_f32_e32 v17, 1.0, v14
	v_add_f32_e32 v18, 1.0, v15
	v_add_f32_e32 v19, 1.0, v16
	v_rcp_f32_e32 v14, v1
	v_rcp_f32_e32 v15, v17
	v_rcp_f32_e32 v16, v18
	v_rcp_f32_e32 v17, v19
	v_pk_mul_f32 v[18:19], v[28:29], v[0:1] op_sel_hi:[1,0]
	v_pk_mul_f32 v[20:21], v[30:31], v[0:1] op_sel_hi:[1,0]
	v_pk_mul_f32 v[12:13], v[14:15], v[12:13]
	v_pk_mul_f32 v[4:5], v[16:17], v[4:5]
	v_pk_mul_f32 v[12:13], v[18:19], v[12:13]
	v_pk_mul_f32 v[4:5], v[20:21], v[4:5]
	v_cvt_pk_bf16_f32 v12, v12, v13
	v_cvt_pk_bf16_f32 v13, v4, v5
	global_store_dwordx2 v[8:9], v[12:13], off offset:64
	v_lshlrev_b32_e32 v12, 16, v248
	v_and_b32_e32 v13, 0xffff0000, v248
	v_lshlrev_b32_e32 v4, 16, v249
	v_and_b32_e32 v5, 0xffff0000, v249
	v_mul_f32_e32 v1, 0xbfb8aa3b, v12
	v_mul_f32_e32 v14, 0xbfb8aa3b, v13
	v_mul_f32_e32 v15, 0xbfb8aa3b, v4
	v_mul_f32_e32 v16, 0xbfb8aa3b, v5
	v_exp_f32_e32 v1, v1
	v_exp_f32_e32 v14, v14
	v_exp_f32_e32 v15, v15
	v_exp_f32_e32 v16, v16
	v_add_f32_e32 v1, 1.0, v1
	v_add_f32_e32 v17, 1.0, v14
	v_add_f32_e32 v18, 1.0, v15
	v_add_f32_e32 v19, 1.0, v16
	v_rcp_f32_e32 v14, v1
	v_rcp_f32_e32 v15, v17
	v_rcp_f32_e32 v16, v18
	v_rcp_f32_e32 v17, v19
	v_pk_mul_f32 v[18:19], v[24:25], v[0:1] op_sel_hi:[1,0]
	v_pk_mul_f32 v[20:21], v[26:27], v[0:1] op_sel_hi:[1,0]
	v_pk_mul_f32 v[12:13], v[14:15], v[12:13]
	v_pk_mul_f32 v[4:5], v[16:17], v[4:5]
	v_pk_mul_f32 v[12:13], v[18:19], v[12:13]
	v_pk_mul_f32 v[4:5], v[20:21], v[4:5]
	v_cvt_pk_bf16_f32 v12, v12, v13
	v_cvt_pk_bf16_f32 v13, v4, v5
	global_store_dwordx2 v[8:9], v[12:13], off offset:96
	s_cbranch_scc0 .LBB0_1190

.LBB0_1060:
	s_or_b64 exec, exec, s[4:5]
	v_max_f32_e32 v24, v24, v24
	v_mov_b32_e32 v25, v24
	s_waitcnt lgkmcnt(0)
	s_nop 1
	v_permlane16_swap_b32_e32 v25, v24
	v_max_f32_e32 v24, v24, v25
	v_mov_b32_e32 v25, v24
	s_nop 1
	v_permlane32_swap_b32_e32 v25, v24
	v_max3_f32 v72, v151, v24, v25
	v_sub_f32_e32 v24, v151, v72
	v_exp_f32_e32 v24, v24
	s_nop 0
	v_mul_f32_e32 v149, v79, v24
	s_and_saveexec_b64 s[4:5], s[2:3]
	s_cbranch_execz .LBB0_1062
	v_sub_f32_e32 v25, v68, v72
	v_exp_f32_e32 v68, v25
	v_sub_f32_e32 v25, v69, v72
	v_exp_f32_e32 v69, v25
	v_sub_f32_e32 v25, v70, v72
	v_exp_f32_e32 v70, v25
	v_sub_f32_e32 v25, v71, v72
	v_exp_f32_e32 v71, v25
	v_add_f32_e32 v25, v68, v149
	v_add_f32_e32 v25, v69, v25
	v_add_f32_e32 v25, v70, v25
	v_add_f32_e32 v149, v71, v25

.LBB0_1095:
	s_or_b64 exec, exec, s[4:5]
	v_max_f32_e32 v153, v153, v153
	v_mov_b32_e32 v200, v153
	s_waitcnt lgkmcnt(0)
	s_nop 1
	v_permlane16_swap_b32_e32 v200, v153
	v_max_f32_e32 v153, v153, v200
	v_mov_b32_e32 v200, v153
	s_nop 1
	v_permlane32_swap_b32_e32 v200, v153
	v_max3_f32 v153, v72, v153, v200
	v_sub_f32_e32 v72, v72, v153
	v_sub_f32_e32 v71, v71, v153
	v_sub_f32_e32 v200, v68, v153
	v_exp_f32_e32 v68, v72
	v_exp_f32_e32 v71, v71
	v_exp_f32_e32 v72, v200
	v_sub_f32_e32 v70, v70, v153
	v_exp_f32_e32 v70, v70
	v_sub_f32_e32 v69, v69, v153
	v_exp_f32_e32 v69, v69
	v_fma_f32 v149, v149, v68, v71
	v_add_f32_e32 v149, v72, v149
	v_add_f32_e32 v149, v70, v149
	v_add_f32_e32 v149, v69, v149
	s_mov_b64 s[4:5], exec
	v_readlane_b32 s18, v240, 15
	v_readlane_b32 s19, v240, 16
	s_and_b64 s[18:19], s[4:5], s[18:19]
	s_mov_b64 exec, s[18:19]
	s_cbranch_execz .LBB0_1097
	v_sub_f32_e32 v38, v38, v153
	v_exp_f32_e32 v38, v38
	v_sub_f32_e32 v37, v37, v153
	v_exp_f32_e32 v37, v37
	v_sub_f32_e32 v36, v36, v153
	v_exp_f32_e32 v36, v36
	v_sub_f32_e32 v39, v39, v153
	v_exp_f32_e32 v39, v39
	v_add_f32_e32 v149, v38, v149
	v_add_f32_e32 v149, v37, v149
	v_add_f32_e32 v149, v36, v149
	v_add_f32_e32 v149, v39, v149

.LBB0_1157:
	s_or_b64 exec, exec, s[64:65]
	v_max_f32_e32 v151, v200, v200
	v_mov_b32_e32 v72, v151
	s_waitcnt lgkmcnt(0)
	s_nop 1
	v_permlane16_swap_b32_e32 v72, v151
	v_max_f32_e32 v72, v151, v72
	v_mov_b32_e32 v151, v72
	s_nop 1
	v_permlane32_swap_b32_e32 v151, v72
	v_max3_f32 v151, v153, v72, v151
	v_sub_f32_e32 v72, v153, v151
	v_exp_f32_e32 v72, v72
	s_nop 0
	v_mul_f32_e32 v149, v149, v72
	s_and_saveexec_b64 s[64:65], s[60:61]
	s_cbranch_execnz .LBB0_1171
	s_or_b64 exec, exec, s[64:65]
	s_and_saveexec_b64 s[60:61], s[92:93]
	s_cbranch_execnz .LBB0_1172

.Lattn_fast:
	v_add_u32_e32 v241, s4, v159
	v_add_u32_e32 v201, v241, v161
	ds_read_b128 v[220:223], v201
	ds_read_b128 v[224:227], v201 offset:64
	ds_read_b128 v[228:231], v201 offset:2304
	ds_read_b128 v[232:235], v201 offset:2368
	ds_read_b128 v[236:239], v201 offset:4608
	ds_read_b128 v[252:255], v201 offset:4672
	s_waitcnt lgkmcnt(4)
	v_mfma_f32_16x16x32_bf16 v[40:43], v[220:223], v[16:19], 0
	v_mfma_f32_16x16x32_bf16 v[40:43], v[224:227], v[20:23], v[40:43]
	ds_read_b128 v[220:223], v201 offset:6912
	ds_read_b128 v[224:227], v201 offset:6976
	s_waitcnt lgkmcnt(4)
	v_mfma_f32_16x16x32_bf16 v[44:47], v[228:231], v[16:19], 0
	v_mfma_f32_16x16x32_bf16 v[44:47], v[232:235], v[20:23], v[44:47]
	ds_read_b128 v[228:231], v201 offset:9216
	ds_read_b128 v[232:235], v201 offset:9280
	s_waitcnt lgkmcnt(4)
	v_mfma_f32_16x16x32_bf16 v[48:51], v[236:239], v[16:19], 0
	v_mfma_f32_16x16x32_bf16 v[48:51], v[252:255], v[20:23], v[48:51]
	ds_read_b128 v[236:239], v201 offset:11520
	ds_read_b128 v[252:255], v201 offset:11584
	s_waitcnt lgkmcnt(4)
	v_mfma_f32_16x16x32_bf16 v[52:55], v[220:223], v[16:19], 0
	v_mfma_f32_16x16x32_bf16 v[52:55], v[224:227], v[20:23], v[52:55]
	ds_read_b128 v[220:223], v201 offset:13824
	ds_read_b128 v[224:227], v201 offset:13888
	s_waitcnt lgkmcnt(4)
	v_mfma_f32_16x16x32_bf16 v[56:59], v[228:231], v[16:19], 0
	v_mfma_f32_16x16x32_bf16 v[56:59], v[232:235], v[20:23], v[56:59]
	ds_read_b128 v[228:231], v201 offset:16128
	ds_read_b128 v[232:235], v201 offset:16192
	s_waitcnt lgkmcnt(4)
	v_mfma_f32_16x16x32_bf16 v[60:63], v[236:239], v[16:19], 0
	v_mfma_f32_16x16x32_bf16 v[60:63], v[252:255], v[20:23], v[60:63]
	s_waitcnt lgkmcnt(2)
	v_mfma_f32_16x16x32_bf16 v[64:67], v[220:223], v[16:19], 0
	v_mfma_f32_16x16x32_bf16 v[64:67], v[224:227], v[20:23], v[64:67]
	s_waitcnt lgkmcnt(0)
	v_mfma_f32_16x16x32_bf16 v[68:71], v[228:231], v[16:19], 0
	v_mfma_f32_16x16x32_bf16 v[68:71], v[232:235], v[20:23], v[68:71]
	s_nop 7
	v_max3_f32 v200, v40, v41, s68
	v_max3_f32 v202, v42, v43, s68
	v_max3_f32 v200, v200, v44, v45
	v_max3_f32 v202, v202, v46, v47
	v_max3_f32 v200, v200, v48, v49
	v_max3_f32 v202, v202, v50, v51
	v_max3_f32 v200, v200, v52, v53
	v_max3_f32 v202, v202, v54, v55
	v_max3_f32 v200, v200, v56, v57
	v_max3_f32 v202, v202, v58, v59
	v_max3_f32 v200, v200, v60, v61
	v_max3_f32 v202, v202, v62, v63
	v_max3_f32 v200, v200, v64, v65
	v_max3_f32 v202, v202, v66, v67
	v_max3_f32 v200, v200, v68, v69
	v_max3_f32 v202, v202, v70, v71
	v_max_f32_e32 v200, v200, v202
	v_max_f32_e32 v151, v200, v200
	v_mov_b32_e32 v72, v151
	s_waitcnt lgkmcnt(0)
	s_nop 1
	v_permlane16_swap_b32_e32 v72, v151
	v_max_f32_e32 v72, v151, v72
	v_mov_b32_e32 v151, v72
	s_nop 1
	v_permlane32_swap_b32_e32 v151, v72
	v_max3_f32 v151, v153, v72, v151
	v_sub_f32_e32 v72, v153, v151
	v_exp_f32_e32 v72, v72
	v_sub_f32_e32 v40, v40, v151
	v_sub_f32_e32 v41, v41, v151
	v_sub_f32_e32 v42, v42, v151
	v_sub_f32_e32 v43, v43, v151
	v_sub_f32_e32 v44, v44, v151
	v_sub_f32_e32 v45, v45, v151
	v_sub_f32_e32 v46, v46, v151
	v_sub_f32_e32 v47, v47, v151
	v_sub_f32_e32 v48, v48, v151
	v_sub_f32_e32 v49, v49, v151
	v_sub_f32_e32 v50, v50, v151
	v_sub_f32_e32 v51, v51, v151
	v_sub_f32_e32 v52, v52, v151
	v_sub_f32_e32 v53, v53, v151
	v_sub_f32_e32 v54, v54, v151
	v_sub_f32_e32 v55, v55, v151
	v_sub_f32_e32 v56, v56, v151
	v_sub_f32_e32 v57, v57, v151
	v_sub_f32_e32 v58, v58, v151
	v_sub_f32_e32 v59, v59, v151
	v_sub_f32_e32 v60, v60, v151
	v_sub_f32_e32 v61, v61, v151
	v_sub_f32_e32 v62, v62, v151
	v_sub_f32_e32 v63, v63, v151
	v_sub_f32_e32 v64, v64, v151
	v_sub_f32_e32 v65, v65, v151
	v_sub_f32_e32 v66, v66, v151
	v_sub_f32_e32 v67, v67, v151
	v_sub_f32_e32 v68, v68, v151
	v_sub_f32_e32 v69, v69, v151
	v_sub_f32_e32 v70, v70, v151
	v_sub_f32_e32 v71, v71, v151
	v_mul_f32_e32 v149, v149, v72
	v_exp_f32_e32 v40, v40
	v_exp_f32_e32 v41, v41
	v_exp_f32_e32 v42, v42
	v_exp_f32_e32 v43, v43
	v_exp_f32_e32 v44, v44
	v_exp_f32_e32 v45, v45
	v_exp_f32_e32 v46, v46
	v_exp_f32_e32 v47, v47
	v_exp_f32_e32 v48, v48
	v_exp_f32_e32 v49, v49
	v_exp_f32_e32 v50, v50
	v_exp_f32_e32 v51, v51
	v_exp_f32_e32 v52, v52
	v_exp_f32_e32 v53, v53
	v_exp_f32_e32 v54, v54
	v_exp_f32_e32 v55, v55
	v_exp_f32_e32 v56, v56
	v_exp_f32_e32 v57, v57
	v_exp_f32_e32 v58, v58
	v_exp_f32_e32 v59, v59
	v_exp_f32_e32 v60, v60
	v_exp_f32_e32 v61, v61
	v_exp_f32_e32 v62, v62
	v_exp_f32_e32 v63, v63
	v_exp_f32_e32 v64, v64
	v_exp_f32_e32 v65, v65
	v_exp_f32_e32 v66, v66
	v_exp_f32_e32 v67, v67
	v_exp_f32_e32 v68, v68
	v_exp_f32_e32 v69, v69
	v_exp_f32_e32 v70, v70
	v_exp_f32_e32 v71, v71
	v_pk_mul_f32 v[38:39], v[38:39], v[72:73] op_sel_hi:[1,0]
	v_pk_mul_f32 v[36:37], v[36:37], v[72:73] op_sel_hi:[1,0]
	v_pk_mul_f32 v[34:35], v[34:35], v[72:73] op_sel_hi:[1,0]
	v_pk_mul_f32 v[32:33], v[32:33], v[72:73] op_sel_hi:[1,0]
	v_pk_mul_f32 v[30:31], v[30:31], v[72:73] op_sel_hi:[1,0]
	v_pk_mul_f32 v[28:29], v[28:29], v[72:73] op_sel_hi:[1,0]
	v_pk_mul_f32 v[26:27], v[26:27], v[72:73] op_sel_hi:[1,0]
	v_pk_mul_f32 v[24:25], v[24:25], v[72:73] op_sel_hi:[1,0]
	v_lshl_add_u32 v241, v160, 1, s38
	v_add_u32_e32 v241, v241, v162
	ds_read_b64_tr_b16 v[220:221], v241
	ds_read_b64_tr_b16 v[222:223], v241 offset:2304
	ds_read_b64_tr_b16 v[224:225], v241 offset:32
	ds_read_b64_tr_b16 v[226:227], v241 offset:2336
	ds_read_b64_tr_b16 v[228:229], v241 offset:64
	ds_read_b64_tr_b16 v[230:231], v241 offset:2368
	ds_read_b64_tr_b16 v[232:233], v241 offset:96
	ds_read_b64_tr_b16 v[234:235], v241 offset:2400
	ds_read_b64_tr_b16 v[236:237], v241 offset:4608
	ds_read_b64_tr_b16 v[238:239], v241 offset:6912
	ds_read_b64_tr_b16 v[252:253], v241 offset:4640
	ds_read_b64_tr_b16 v[254:255], v241 offset:6944
	v_add_f32_e32 v149, v40, v149
	v_add_f32_e32 v149, v41, v149
	v_add_f32_e32 v149, v42, v149
	v_add_f32_e32 v149, v43, v149
	v_add_f32_e32 v149, v44, v149
	v_add_f32_e32 v149, v45, v149
	v_add_f32_e32 v149, v46, v149
	v_add_f32_e32 v149, v47, v149
	v_add_f32_e32 v149, v48, v149
	v_add_f32_e32 v149, v49, v149
	v_add_f32_e32 v149, v50, v149
	v_add_f32_e32 v149, v51, v149
	v_add_f32_e32 v149, v52, v149
	v_add_f32_e32 v149, v53, v149
	v_add_f32_e32 v149, v54, v149
	v_add_f32_e32 v149, v55, v149
	v_add_f32_e32 v149, v56, v149
	v_add_f32_e32 v149, v57, v149
	v_add_f32_e32 v149, v58, v149
	v_add_f32_e32 v149, v59, v149
	v_add_f32_e32 v149, v60, v149
	v_add_f32_e32 v149, v61, v149
	v_add_f32_e32 v149, v62, v149
	v_add_f32_e32 v149, v63, v149
	v_add_f32_e32 v149, v64, v149
	v_add_f32_e32 v149, v65, v149
	v_add_f32_e32 v149, v66, v149
	v_add_f32_e32 v149, v67, v149
	v_add_f32_e32 v149, v68, v149
	v_add_f32_e32 v149, v69, v149
	v_add_f32_e32 v149, v70, v149
	v_add_f32_e32 v149, v71, v149
	v_cvt_pk_bf16_f32 v40, v40, v41
	v_cvt_pk_bf16_f32 v41, v42, v43
	v_cvt_pk_bf16_f32 v42, v44, v45
	v_cvt_pk_bf16_f32 v43, v46, v47
	v_cvt_pk_bf16_f32 v48, v48, v49
	v_cvt_pk_bf16_f32 v49, v50, v51
	v_cvt_pk_bf16_f32 v50, v52, v53
	v_cvt_pk_bf16_f32 v51, v54, v55
	v_cvt_pk_bf16_f32 v56, v56, v57
	v_cvt_pk_bf16_f32 v57, v58, v59
	v_cvt_pk_bf16_f32 v58, v60, v61
	v_cvt_pk_bf16_f32 v59, v62, v63
	v_cvt_pk_bf16_f32 v64, v64, v65
	v_cvt_pk_bf16_f32 v65, v66, v67
	v_cvt_pk_bf16_f32 v66, v68, v69
	v_cvt_pk_bf16_f32 v67, v70, v71
	s_nop 1
	s_waitcnt lgkmcnt(10)
	v_mfma_f32_16x16x32_bf16 v[36:39], v[220:223], v[40:43], v[36:39]
	ds_read_b64_tr_b16 v[220:221], v241 offset:4672
	ds_read_b64_tr_b16 v[222:223], v241 offset:6976
	s_waitcnt lgkmcnt(10)
	v_mfma_f32_16x16x32_bf16 v[32:35], v[224:227], v[40:43], v[32:35]
	ds_read_b64_tr_b16 v[224:225], v241 offset:4704
	ds_read_b64_tr_b16 v[226:227], v241 offset:7008
	s_waitcnt lgkmcnt(10)
	v_mfma_f32_16x16x32_bf16 v[28:31], v[228:231], v[40:43], v[28:31]
	ds_read_b64_tr_b16 v[228:229], v241 offset:9216
	ds_read_b64_tr_b16 v[230:231], v241 offset:11520
	s_waitcnt lgkmcnt(10)
	v_mfma_f32_16x16x32_bf16 v[24:27], v[232:235], v[40:43], v[24:27]
	ds_read_b64_tr_b16 v[232:233], v241 offset:9248
	ds_read_b64_tr_b16 v[234:235], v241 offset:11552
	s_waitcnt lgkmcnt(10)
	v_mfma_f32_16x16x32_bf16 v[36:39], v[236:239], v[48:51], v[36:39]
	ds_read_b64_tr_b16 v[236:237], v241 offset:9280
	ds_read_b64_tr_b16 v[238:239], v241 offset:11584
	s_waitcnt lgkmcnt(10)
	v_mfma_f32_16x16x32_bf16 v[32:35], v[252:255], v[48:51], v[32:35]
	ds_read_b64_tr_b16 v[252:253], v241 offset:9312
	ds_read_b64_tr_b16 v[254:255], v241 offset:11616
	s_waitcnt lgkmcnt(10)
	v_mfma_f32_16x16x32_bf16 v[28:31], v[220:223], v[48:51], v[28:31]
	ds_read_b64_tr_b16 v[220:221], v241 offset:13824
	ds_read_b64_tr_b16 v[222:223], v241 offset:16128
	s_waitcnt lgkmcnt(10)
	v_mfma_f32_16x16x32_bf16 v[24:27], v[224:227], v[48:51], v[24:27]
	ds_read_b64_tr_b16 v[224:225], v241 offset:13856
	ds_read_b64_tr_b16 v[226:227], v241 offset:16160
	s_waitcnt lgkmcnt(10)
	v_mfma_f32_16x16x32_bf16 v[36:39], v[228:231], v[56:59], v[36:39]
	ds_read_b64_tr_b16 v[228:229], v241 offset:13888
	ds_read_b64_tr_b16 v[230:231], v241 offset:16192
	s_waitcnt lgkmcnt(10)
	v_mfma_f32_16x16x32_bf16 v[32:35], v[232:235], v[56:59], v[32:35]
	ds_read_b64_tr_b16 v[232:233], v241 offset:13920
	ds_read_b64_tr_b16 v[234:235], v241 offset:16224
	s_waitcnt lgkmcnt(10)
	v_mfma_f32_16x16x32_bf16 v[28:31], v[236:239], v[56:59], v[28:31]
	s_waitcnt lgkmcnt(8)
	v_mfma_f32_16x16x32_bf16 v[24:27], v[252:255], v[56:59], v[24:27]
	s_waitcnt lgkmcnt(6)
	v_mfma_f32_16x16x32_bf16 v[36:39], v[220:223], v[64:67], v[36:39]
	s_waitcnt lgkmcnt(4)
	v_mfma_f32_16x16x32_bf16 v[32:35], v[224:227], v[64:67], v[32:35]
	s_waitcnt lgkmcnt(2)
	v_mfma_f32_16x16x32_bf16 v[28:31], v[228:231], v[64:67], v[28:31]
	s_waitcnt lgkmcnt(0)
	v_mfma_f32_16x16x32_bf16 v[24:27], v[232:235], v[64:67], v[24:27]
	s_nop 7
	s_branch .LBB0_1170

.LBB0_2292:
	ds_read_b128 v[102:105], v205 offset:6144
	ds_read_b128 v[106:109], v205 offset:6160
	s_waitcnt vmcnt(6)
	v_lshlrev_b32_e32 v142, 16, v98
	v_and_b32_e32 v143, 0xffff0000, v98
	s_waitcnt lgkmcnt(1)
	v_mul_f32_e32 v0, 0xbfb8aa3b, v102
	v_exp_f32_e32 v140, v0
	v_mul_f32_e32 v0, 0xbfb8aa3b, v103
	v_exp_f32_e32 v141, v0
	v_mul_f32_e32 v0, 0xbfb8aa3b, v104
	v_pk_mul_f32 v[140:141], v[140:141], v[142:143]
	s_nop 0
	v_cvt_pk_bf16_f32 v98, v140, v141
	v_exp_f32_e32 v140, v0
	v_mul_f32_e32 v0, 0xbfb8aa3b, v105
	v_exp_f32_e32 v141, v0
	v_lshlrev_b32_e32 v142, 16, v99
	v_and_b32_e32 v143, 0xffff0000, v99
	s_waitcnt lgkmcnt(0)
	v_mul_f32_e32 v0, 0xbfb8aa3b, v106
	v_pk_mul_f32 v[140:141], v[140:141], v[142:143]
	v_lshlrev_b32_e32 v142, 16, v100
	v_cvt_pk_bf16_f32 v99, v140, v141
	v_exp_f32_e32 v140, v0
	v_mul_f32_e32 v0, 0xbfb8aa3b, v107
	v_exp_f32_e32 v141, v0
	v_and_b32_e32 v143, 0xffff0000, v100
	v_mul_f32_e32 v0, 0xbfb8aa3b, v108
	v_pk_mul_f32 v[140:141], v[140:141], v[142:143]
	s_nop 0
	v_cvt_pk_bf16_f32 v100, v140, v141
	v_exp_f32_e32 v140, v0
	v_mul_f32_e32 v0, 0xbfb8aa3b, v109
	v_exp_f32_e32 v141, v0
	v_lshlrev_b32_e32 v142, 16, v101
	v_and_b32_e32 v143, 0xffff0000, v101
	v_mul_f32_e32 v0, 0x3fb8aa3b, v102
	v_pk_mul_f32 v[140:141], v[140:141], v[142:143]
	s_nop 0
	v_cvt_pk_bf16_f32 v101, v140, v141
	ds_write_b128 v184, v[98:101] offset:56320
	v_exp_f32_e32 v98, v0
	v_mul_f32_e32 v0, 0x3fb8aa3b, v103
	v_exp_f32_e32 v99, v0
	v_lshlrev_b32_e32 v100, 16, v94
	v_and_b32_e32 v101, 0xffff0000, v94
	v_mul_f32_e32 v0, 0x3fb8aa3b, v104
	v_pk_mul_f32 v[98:99], v[98:99], s[48:49] op_sel_hi:[1,0]
	s_waitcnt vmcnt(4)
	v_lshlrev_b32_e32 v104, 16, v90
	v_pk_mul_f32 v[98:99], v[98:99], v[100:101]
	v_lshlrev_b32_e32 v100, 16, v95
	v_cvt_pk_bf16_f32 v94, v98, v99
	v_exp_f32_e32 v98, v0
	v_mul_f32_e32 v0, 0x3fb8aa3b, v105
	v_exp_f32_e32 v99, v0
	v_and_b32_e32 v101, 0xffff0000, v95
	v_mul_f32_e32 v0, 0x3fb8aa3b, v106
	v_and_b32_e32 v105, 0xffff0000, v90
	v_pk_mul_f32 v[98:99], v[98:99], s[48:49] op_sel_hi:[1,0]
	s_nop 0
	v_pk_mul_f32 v[98:99], v[98:99], v[100:101]
	v_lshlrev_b32_e32 v100, 16, v96
	v_cvt_pk_bf16_f32 v95, v98, v99
	v_exp_f32_e32 v98, v0
	v_mul_f32_e32 v0, 0x3fb8aa3b, v107
	v_exp_f32_e32 v99, v0
	v_and_b32_e32 v101, 0xffff0000, v96
	v_mul_f32_e32 v0, 0x3fb8aa3b, v108
	v_pk_mul_f32 v[98:99], v[98:99], s[48:49] op_sel_hi:[1,0]
	s_nop 0
	v_pk_mul_f32 v[98:99], v[98:99], v[100:101]
	v_lshlrev_b32_e32 v100, 16, v97
	v_cvt_pk_bf16_f32 v96, v98, v99
	v_exp_f32_e32 v98, v0
	v_mul_f32_e32 v0, 0x3fb8aa3b, v109
	v_exp_f32_e32 v99, v0
	v_and_b32_e32 v101, 0xffff0000, v97
	v_pk_mul_f32 v[98:99], v[98:99], s[48:49] op_sel_hi:[1,0]
	s_nop 0
	v_pk_mul_f32 v[98:99], v[98:99], v[100:101]
	s_nop 0
	v_cvt_pk_bf16_f32 v97, v98, v99
	ds_write_b128 v184, v[94:97] offset:38912
	ds_read_b128 v[94:97], v206 offset:6144
	ds_read_b128 v[98:101], v206 offset:6160
	s_waitcnt lgkmcnt(1)
	v_mul_f32_e32 v0, 0xbfb8aa3b, v94
	v_exp_f32_e32 v102, v0
	v_mul_f32_e32 v0, 0xbfb8aa3b, v95
	v_exp_f32_e32 v103, v0
	v_mul_f32_e32 v0, 0xbfb8aa3b, v96
	v_pk_mul_f32 v[102:103], v[102:103], v[104:105]
	s_nop 0
	v_cvt_pk_bf16_f32 v90, v102, v103
	v_exp_f32_e32 v102, v0
	v_mul_f32_e32 v0, 0xbfb8aa3b, v97
	v_exp_f32_e32 v103, v0
	v_lshlrev_b32_e32 v104, 16, v91
	v_and_b32_e32 v105, 0xffff0000, v91
	s_waitcnt lgkmcnt(0)
	v_mul_f32_e32 v0, 0xbfb8aa3b, v98
	v_pk_mul_f32 v[102:103], v[102:103], v[104:105]
	v_lshlrev_b32_e32 v104, 16, v92
	v_cvt_pk_bf16_f32 v91, v102, v103
	v_exp_f32_e32 v102, v0
	v_mul_f32_e32 v0, 0xbfb8aa3b, v99
	v_exp_f32_e32 v103, v0
	v_and_b32_e32 v105, 0xffff0000, v92
	v_mul_f32_e32 v0, 0xbfb8aa3b, v100
	v_pk_mul_f32 v[102:103], v[102:103], v[104:105]
	s_nop 0
	v_cvt_pk_bf16_f32 v92, v102, v103
	v_exp_f32_e32 v102, v0
	v_mul_f32_e32 v0, 0xbfb8aa3b, v101
	v_exp_f32_e32 v103, v0
	v_lshlrev_b32_e32 v104, 16, v93
	v_and_b32_e32 v105, 0xffff0000, v93
	v_mul_f32_e32 v0, 0x3fb8aa3b, v94
	v_pk_mul_f32 v[102:103], v[102:103], v[104:105]
	s_nop 0
	v_cvt_pk_bf16_f32 v93, v102, v103
	ds_write_b128 v185, v[90:93] offset:56320
	v_exp_f32_e32 v90, v0
	v_mul_f32_e32 v0, 0x3fb8aa3b, v95
	v_exp_f32_e32 v91, v0
	v_lshlrev_b32_e32 v92, 16, v70
	v_and_b32_e32 v93, 0xffff0000, v70
	v_mul_f32_e32 v0, 0x3fb8aa3b, v96
	v_pk_mul_f32 v[90:91], v[90:91], s[48:49] op_sel_hi:[1,0]
	s_nop 0
	v_pk_mul_f32 v[90:91], v[90:91], v[92:93]
	v_lshlrev_b32_e32 v92, 16, v71
	v_cvt_pk_bf16_f32 v70, v90, v91
	v_exp_f32_e32 v90, v0
	v_mul_f32_e32 v0, 0x3fb8aa3b, v97
	v_exp_f32_e32 v91, v0
	v_and_b32_e32 v93, 0xffff0000, v71
	v_mul_f32_e32 v0, 0x3fb8aa3b, v98
	v_pk_mul_f32 v[90:91], v[90:91], s[48:49] op_sel_hi:[1,0]
	s_nop 0
	v_pk_mul_f32 v[90:91], v[90:91], v[92:93]
	v_lshlrev_b32_e32 v92, 16, v72
	v_cvt_pk_bf16_f32 v71, v90, v91
	v_exp_f32_e32 v90, v0
	v_mul_f32_e32 v0, 0x3fb8aa3b, v99
	v_exp_f32_e32 v91, v0
	v_and_b32_e32 v93, 0xffff0000, v72
	v_mul_f32_e32 v0, 0x3fb8aa3b, v100
	v_pk_mul_f32 v[90:91], v[90:91], s[48:49] op_sel_hi:[1,0]
	s_nop 0
	v_pk_mul_f32 v[90:91], v[90:91], v[92:93]
	v_lshlrev_b32_e32 v92, 16, v73
	v_cvt_pk_bf16_f32 v72, v90, v91
	v_exp_f32_e32 v90, v0
	v_mul_f32_e32 v0, 0x3fb8aa3b, v101
	v_exp_f32_e32 v91, v0
	v_and_b32_e32 v93, 0xffff0000, v73
	v_pk_mul_f32 v[90:91], v[90:91], s[48:49] op_sel_hi:[1,0]
	s_nop 0
	v_pk_mul_f32 v[90:91], v[90:91], v[92:93]
	s_nop 0
	v_cvt_pk_bf16_f32 v73, v90, v91
	ds_write_b128 v185, v[70:73] offset:38912
	s_waitcnt vmcnt(3)
	ds_write_b128 v207, v[74:77]
	s_waitcnt vmcnt(2)
	ds_write_b128 v208, v[78:81]
	s_waitcnt vmcnt(1)
	ds_write_b128 v207, v[82:85] offset:16896
	s_waitcnt vmcnt(0)
	ds_write_b128 v209, v[86:89]
	v_lshl_add_u64 v[70:71], s[56:57], 0, v[118:119]
	v_lshl_add_u64 v[72:73], s[56:57], 0, v[122:123]
	v_lshl_add_u64 v[74:75], s[56:57], 0, v[124:125]
	global_load_dwordx2 v[160:161], v[70:71], off
	global_load_dwordx2 v[158:159], v[70:71], off offset:32
	global_load_dwordx2 v[152:153], v[72:73], off
	global_load_dwordx2 v[150:151], v[74:75], off
	v_lshl_add_u64 v[70:71], s[56:57], 0, v[126:127]
	v_lshl_add_u64 v[72:73], s[56:57], 0, v[128:129]
	v_lshl_add_u64 v[74:75], s[56:57], 0, v[130:131]
	v_lshl_add_u64 v[76:77], s[56:57], 0, v[132:133]
	global_load_dwordx2 v[148:149], v[70:71], off
	global_load_dwordx2 v[146:147], v[72:73], off
	global_load_dwordx2 v[142:143], v[74:75], off
	global_load_dwordx2 v[140:141], v[76:77], off
	s_waitcnt lgkmcnt(0)
	s_barrier
	ds_read_b128 v[70:73], v210 offset:56320
	ds_read_b128 v[74:77], v183 offset:38912
	ds_read_b128 v[78:81], v210 offset:56384
	ds_read_b128 v[82:85], v183 offset:38976
	s_waitcnt lgkmcnt(2)
	v_mfma_f32_16x16x32_bf16 v[70:73], v[70:73], v[74:77], 0
	v_mov_b32_e32 v0, s93
	v_cvt_pk_bf16_f32 v170, v62, v63
	v_cvt_pk_bf16_f32 v171, v64, v65
	s_waitcnt lgkmcnt(0)
	v_mfma_f32_16x16x32_bf16 v[70:73], v[78:81], v[82:85], v[70:73]
	ds_read_b128 v[78:81], v210 offset:56448
	ds_read_b128 v[86:89], v183 offset:39040
	v_cvt_pk_bf16_f32 v172, v66, v67
	v_cvt_pk_bf16_f32 v173, v68, v69
	s_waitcnt lgkmcnt(0)
	v_mfma_f32_16x16x32_bf16 v[70:73], v[78:81], v[86:89], v[70:73]
	ds_read_b128 v[78:81], v210 offset:56512
	ds_read_b128 v[90:93], v183 offset:39104
	s_add_u32 s49, s49, s0
	s_addc_u32 s53, s69, 0
	s_waitcnt lgkmcnt(0)
	v_mfma_f32_16x16x32_bf16 v[70:73], v[78:81], v[90:93], v[70:73]
	s_add_u32 s60, s49, 0xafc1000
	s_addc_u32 s61, s53, 0
	s_waitcnt vmcnt(7)
	v_lshlrev_b32_e32 v228, 16, v160
	s_nop 3
	v_cndmask_b32_e64 v0, v70, v0, s[14:15]
	v_cndmask_b32_e64 v70, v71, 0, s[30:31]
	v_cndmask_b32_e64 v71, v72, 0, s[34:35]
	v_cndmask_b32_e64 v72, v73, 0, s[36:37]
	v_cvt_pk_bf16_f32 v70, v0, v70
	v_cvt_pk_bf16_f32 v71, v71, v72
	ds_write_b64 v211, v[70:71]
	ds_read_b128 v[70:73], v212 offset:56320
	s_waitcnt lgkmcnt(0)
	v_mfma_f32_16x16x32_bf16 v[70:73], v[70:73], v[74:77], 0
	ds_read_b128 v[74:77], v212 offset:56384
	v_mov_b32_e32 v0, s93
	v_and_b32_e32 v229, 0xffff0000, v160
	s_waitcnt lgkmcnt(0)
	v_mfma_f32_16x16x32_bf16 v[70:73], v[74:77], v[82:85], v[70:73]
	ds_read_b128 v[74:77], v212 offset:56448
	v_lshlrev_b32_e32 v160, 16, v161
	v_and_b32_e32 v161, 0xffff0000, v161
	s_waitcnt lgkmcnt(0)
	v_mfma_f32_16x16x32_bf16 v[70:73], v[74:77], v[86:89], v[70:73]
	ds_read_b128 v[74:77], v212 offset:56512
	s_waitcnt vmcnt(6)
	v_lshlrev_b32_e32 v230, 16, v158
	v_and_b32_e32 v231, 0xffff0000, v158
	s_waitcnt lgkmcnt(0)
	v_mfma_f32_16x16x32_bf16 v[70:73], v[74:77], v[90:93], v[70:73]
	v_lshlrev_b32_e32 v158, 16, v159
	v_and_b32_e32 v159, 0xffff0000, v159
	s_nop 5
	v_cndmask_b32_e64 v0, v70, v0, s[22:23]
	v_cndmask_b32_e64 v70, v71, 0, s[38:39]
	v_cndmask_b32_e64 v71, v72, 0, s[40:41]
	v_cndmask_b32_e64 v72, v73, 0, s[42:43]
	v_cvt_pk_bf16_f32 v70, v0, v70
	v_cvt_pk_bf16_f32 v71, v71, v72
	ds_write_b64 v213, v[70:71]
	s_waitcnt lgkmcnt(0)
	s_barrier
	ds_read_b64_tr_b16 v[72:73], v214 offset:2112
	ds_read_b64_tr_b16 v[70:71], v214
	ds_read_b64_tr_b16 v[74:75], v214 offset:32
	ds_read_b64_tr_b16 v[78:79], v214 offset:16896
	ds_read_b64_tr_b16 v[80:81], v214 offset:19008
	ds_read_b64_tr_b16 v[76:77], v214 offset:2144
	ds_read_b64_tr_b16 v[82:83], v214 offset:16928
	ds_read_b64_tr_b16 v[84:85], v214 offset:19040
	ds_read_b128 v[86:89], v215
	ds_read_b128 v[94:97], v215 offset:64
	ds_read_b128 v[102:105], v215 offset:2368
	s_waitcnt lgkmcnt(2)
	v_mfma_f32_16x16x32_bf16 v[90:93], v[70:73], v[86:89], 0
	ds_read_b128 v[162:165], v215 offset:4672
	v_mfma_f32_16x16x32_bf16 v[86:89], v[74:77], v[86:89], 0
	s_waitcnt lgkmcnt(2)
	v_mfma_f32_16x16x32_bf16 v[90:93], v[78:81], v[94:97], v[90:93]
	v_mfma_f32_16x16x32_bf16 v[86:89], v[82:85], v[94:97], v[86:89]
	ds_read_b128 v[94:97], v215 offset:2304
	s_waitcnt lgkmcnt(0)
	v_mfma_f32_16x16x32_bf16 v[98:101], v[70:73], v[94:97], 0
	v_mfma_f32_16x16x32_bf16 v[94:97], v[74:77], v[94:97], 0
	v_mfma_f32_16x16x32_bf16 v[98:101], v[78:81], v[102:105], v[98:101]
	v_mfma_f32_16x16x32_bf16 v[94:97], v[82:85], v[102:105], v[94:97]
	ds_read_b128 v[102:105], v215 offset:4608
	s_waitcnt lgkmcnt(0)
	v_mfma_f32_16x16x32_bf16 v[106:109], v[70:73], v[102:105], 0
	v_mfma_f32_16x16x32_bf16 v[102:105], v[74:77], v[102:105], 0
	v_mfma_f32_16x16x32_bf16 v[106:109], v[78:81], v[162:165], v[106:109]
	v_mfma_f32_16x16x32_bf16 v[102:105], v[82:85], v[162:165], v[102:105]
	ds_read_b128 v[162:165], v215 offset:6912
	s_waitcnt lgkmcnt(0)
	v_mfma_f32_16x16x32_bf16 v[70:73], v[70:73], v[162:165], 0
	v_mfma_f32_16x16x32_bf16 v[74:77], v[74:77], v[162:165], 0
	ds_read_b128 v[162:165], v215 offset:6976
	s_waitcnt lgkmcnt(0)
	v_mfma_f32_16x16x32_bf16 v[70:73], v[78:81], v[162:165], v[70:73]
	v_cvt_pk_bf16_f32 v78, v30, v31
	v_cvt_pk_bf16_f32 v79, v32, v33
	v_cvt_pk_bf16_f32 v80, v10, v11
	v_mfma_f32_16x16x32_bf16 v[74:77], v[82:85], v[162:165], v[74:77]
	v_cvt_pk_bf16_f32 v81, v12, v13
	v_cvt_pk_bf16_f32 v82, v6, v7
	v_cvt_pk_bf16_f32 v83, v8, v9
	v_cvt_pk_bf16_f32 v84, v18, v19
	v_cvt_pk_bf16_f32 v85, v20, v21
	ds_read2_b64 v[162:165], v219 offset1:4
	s_waitcnt lgkmcnt(0)
	v_mfma_f32_16x16x32_bf16 v[90:93], v[78:81], v[162:165], v[90:93]
	v_mfma_f32_16x16x32_bf16 v[86:89], v[82:85], v[162:165], v[86:89]
	ds_read2_b64 v[162:165], v220 offset0:32 offset1:36
	s_waitcnt lgkmcnt(0)
	v_mfma_f32_16x16x32_bf16 v[98:101], v[78:81], v[162:165], v[98:101]
	v_mfma_f32_16x16x32_bf16 v[94:97], v[82:85], v[162:165], v[94:97]
	ds_read2_b64 v[162:165], v221 offset0:64 offset1:68
	s_waitcnt lgkmcnt(0)
	v_mfma_f32_16x16x32_bf16 v[106:109], v[78:81], v[162:165], v[106:109]
	v_mfma_f32_16x16x32_bf16 v[102:105], v[82:85], v[162:165], v[102:105]
	ds_read2_b64 v[162:165], v222 offset0:96 offset1:100
	s_waitcnt lgkmcnt(0)
	v_mfma_f32_16x16x32_bf16 v[70:73], v[78:81], v[162:165], v[70:73]
	v_cvt_pk_bf16_f32 v78, v14, v15
	v_cvt_pk_bf16_f32 v79, v16, v17
	v_cvt_pk_bf16_f32 v80, v38, v39
	v_mfma_f32_16x16x32_bf16 v[74:77], v[82:85], v[162:165], v[74:77]
	v_cvt_pk_bf16_f32 v81, v40, v41
	v_cvt_pk_bf16_f32 v82, v26, v27
	v_cvt_pk_bf16_f32 v83, v28, v29
	v_cvt_pk_bf16_f32 v84, v50, v51
	v_cvt_pk_bf16_f32 v85, v52, v53
	ds_read2_b64 v[162:165], v219 offset0:8 offset1:12
	s_waitcnt lgkmcnt(0)
	v_mfma_f32_16x16x32_bf16 v[90:93], v[78:81], v[162:165], v[90:93]
	v_mfma_f32_16x16x32_bf16 v[86:89], v[82:85], v[162:165], v[86:89]
	ds_read2_b64 v[162:165], v220 offset0:40 offset1:44
	s_waitcnt lgkmcnt(0)
	v_mfma_f32_16x16x32_bf16 v[98:101], v[78:81], v[162:165], v[98:101]
	v_mfma_f32_16x16x32_bf16 v[94:97], v[82:85], v[162:165], v[94:97]
	ds_read2_b64 v[162:165], v221 offset0:72 offset1:76
	s_waitcnt lgkmcnt(0)
	v_mfma_f32_16x16x32_bf16 v[106:109], v[78:81], v[162:165], v[106:109]
	v_mfma_f32_16x16x32_bf16 v[102:105], v[82:85], v[162:165], v[102:105]
	ds_read2_b64 v[162:165], v222 offset0:104 offset1:108
	s_waitcnt lgkmcnt(0)
	v_mfma_f32_16x16x32_bf16 v[70:73], v[78:81], v[162:165], v[70:73]
	v_cvt_pk_bf16_f32 v78, v22, v23
	v_cvt_pk_bf16_f32 v79, v24, v25
	v_cvt_pk_bf16_f32 v80, v42, v43
	v_mfma_f32_16x16x32_bf16 v[74:77], v[82:85], v[162:165], v[74:77]
	v_cvt_pk_bf16_f32 v81, v44, v45
	v_cvt_pk_bf16_f32 v82, v34, v35
	v_cvt_pk_bf16_f32 v83, v36, v37
	v_cvt_pk_bf16_f32 v84, v54, v55
	v_cvt_pk_bf16_f32 v85, v56, v57
	ds_read2_b64 v[162:165], v219 offset0:16 offset1:20
	s_waitcnt lgkmcnt(0)
	v_mfma_f32_16x16x32_bf16 v[90:93], v[78:81], v[162:165], v[90:93]
	v_mfma_f32_16x16x32_bf16 v[86:89], v[82:85], v[162:165], v[86:89]
	ds_read2_b64 v[162:165], v220 offset0:48 offset1:52
	s_waitcnt lgkmcnt(0)
	v_mfma_f32_16x16x32_bf16 v[98:101], v[78:81], v[162:165], v[98:101]
	v_mfma_f32_16x16x32_bf16 v[94:97], v[82:85], v[162:165], v[94:97]
	ds_read2_b64 v[162:165], v221 offset0:80 offset1:84
	s_waitcnt lgkmcnt(0)
	v_mfma_f32_16x16x32_bf16 v[166:169], v[78:81], v[162:165], v[106:109]
	v_mfma_f32_16x16x32_bf16 v[162:165], v[82:85], v[162:165], v[102:105]
	s_nop 2
	ds_read2_b64 v[102:105], v222 offset0:112 offset1:116
	s_waitcnt lgkmcnt(0)
	v_mfma_f32_16x16x32_bf16 v[70:73], v[78:81], v[102:105], v[70:73]
	v_cvt_pk_bf16_f32 v78, v46, v47
	v_cvt_pk_bf16_f32 v79, v48, v49
	v_cvt_pk_bf16_f32 v80, v58, v59
	v_mfma_f32_16x16x32_bf16 v[74:77], v[82:85], v[102:105], v[74:77]
	v_cvt_pk_bf16_f32 v81, v60, v61
	ds_read2_b64 v[82:85], v219 offset0:24 offset1:28
	s_waitcnt lgkmcnt(0)
	v_mfma_f32_16x16x32_bf16 v[106:109], v[78:81], v[82:85], v[90:93]
	v_mfma_f32_16x16x32_bf16 v[102:105], v[170:173], v[82:85], v[86:89]
	ds_read2_b64 v[82:85], v220 offset0:56 offset1:60
	s_nop 5
	v_pk_add_f32 v[106:107], v[106:107], v[228:229]
	v_pk_add_f32 v[108:109], v[108:109], v[160:161]
	s_waitcnt lgkmcnt(0)
	v_mfma_f32_16x16x32_bf16 v[98:101], v[78:81], v[82:85], v[98:101]
	v_mul_f32_e64 v160, v106, v106
	v_mul_f32_e64 v161, v107, v107
	v_pk_mul_f32 v[228:229], v[108:109], v[108:109]
	v_add_f32_e32 v0, v160, v161
	v_mfma_f32_16x16x32_bf16 v[94:97], v[170:173], v[82:85], v[94:97]
	ds_read2_b64 v[82:85], v221 offset0:88 offset1:92
	v_pk_add_f32 v[102:103], v[102:103], v[230:231]
	v_add_f32_e32 v0, v228, v0
	s_waitcnt lgkmcnt(0)
	v_mfma_f32_16x16x32_bf16 v[86:89], v[170:173], v[82:85], v[162:165]
	v_add_f32_e64 v104, v104, v158
	v_add_f32_e64 v105, v105, v159
	s_nop 0
	ds_read2_b64 v[162:165], v222 offset0:120 offset1:124
	v_pk_mul_f32 v[158:159], v[102:103], v[102:103]
	v_mfma_f32_16x16x32_bf16 v[90:93], v[78:81], v[82:85], v[166:169]
	v_add_f32_e32 v0, v229, v0
	v_add_f32_e32 v0, v158, v0
	v_pk_mul_f32 v[230:231], v[104:105], v[104:105]
	s_waitcnt lgkmcnt(0)
	v_mfma_f32_16x16x32_bf16 v[82:85], v[78:81], v[162:165], v[70:73]
	v_add_f32_e32 v0, v159, v0
	v_add_f32_e32 v0, v230, v0
	v_add_f32_e32 v0, v231, v0
	v_lshl_add_u64 v[70:71], s[60:61], 0, v[120:121]
	v_add_co_u32_e32 v72, vcc, s81, v70
	v_mfma_f32_16x16x32_bf16 v[78:81], v[170:173], v[162:165], v[74:77]
	s_nop 0
	v_addc_co_u32_e32 v73, vcc, 0, v71, vcc
	global_load_dwordx2 v[172:173], v[70:71], off
	global_load_dwordx2 v[170:171], v[70:71], off offset:32
	global_load_dwordx2 v[168:169], v[72:73], off
	global_load_dwordx2 v[166:167], v[72:73], off offset:32
	v_add_co_u32_e32 v72, vcc, s72, v70
	v_mov_b32_e32 v135, v0
	s_nop 1
	v_permlane16_swap_b32_e32 v135, v0
	s_nop 0
	v_addc_co_u32_e32 v73, vcc, 0, v71, vcc
	v_add_co_u32_e32 v70, vcc, s73, v70
	global_load_dwordx2 v[164:165], v[72:73], off
	global_load_dwordx2 v[162:163], v[72:73], off offset:32
	v_addc_co_u32_e32 v71, vcc, 0, v71, vcc
	global_load_dwordx2 v[156:157], v[70:71], off
	global_load_dwordx2 v[144:145], v[70:71], off offset:32
	global_load_dwordx4 v[74:77], v[138:139], off
	s_nop 0
	global_load_dwordx4 v[70:73], v[138:139], off offset:64
	s_waitcnt lgkmcnt(0)
	v_add_f32_e32 v0, v0, v135
	v_mov_b32_e32 v135, v0
	s_nop 1
	v_permlane32_swap_b32_e32 v135, v0
	s_and_saveexec_b64 s[60:61], s[4:5]
	s_cbranch_execz .LBB0_2294
	s_waitcnt lgkmcnt(0)
	v_add_f32_e32 v0, v0, v135
	ds_write_b32 v189, v0
.LBB0_2294:
	s_or_b64 exec, exec, s[60:61]
	s_waitcnt vmcnt(15)
	v_lshlrev_b32_e32 v158, 16, v152
	v_and_b32_e32 v159, 0xffff0000, v152
	v_pk_add_f32 v[158:159], v[98:99], v[158:159]
	v_lshlrev_b32_e32 v98, 16, v153
	v_and_b32_e32 v99, 0xffff0000, v153
	v_pk_add_f32 v[100:101], v[100:101], v[98:99]
	v_pk_mul_f32 v[152:153], v[158:159], v[158:159]
	v_pk_mul_f32 v[160:161], v[100:101], v[100:101]
	s_waitcnt vmcnt(14)
	v_lshlrev_b32_e32 v98, 16, v150
	v_and_b32_e32 v99, 0xffff0000, v150
	v_add_f32_e32 v0, v152, v153
	v_pk_add_f32 v[98:99], v[94:95], v[98:99]
	v_lshlrev_b32_e32 v94, 16, v151
	v_and_b32_e32 v95, 0xffff0000, v151
	v_add_f32_e32 v0, v160, v0
	v_pk_add_f32 v[96:97], v[96:97], v[94:95]
	v_pk_mul_f32 v[94:95], v[98:99], v[98:99]
	v_add_f32_e32 v0, v161, v0
	v_add_f32_e32 v0, v94, v0
	v_pk_mul_f32 v[150:151], v[96:97], v[96:97]
	v_add_f32_e32 v0, v95, v0
	v_add_f32_e32 v0, v150, v0
	v_add_f32_e32 v0, v151, v0
	v_mov_b32_e32 v94, v0
	s_nop 1
	v_permlane16_swap_b32_e32 v94, v0
	s_waitcnt lgkmcnt(0)
	v_add_f32_e32 v0, v0, v94
	v_mov_b32_e32 v94, v0
	s_nop 1
	v_permlane32_swap_b32_e32 v94, v0
	s_and_saveexec_b64 s[60:61], s[4:5]
	s_cbranch_execz .LBB0_2296
	s_waitcnt lgkmcnt(0)
	v_add_f32_e32 v0, v0, v94
	ds_write_b32 v189, v0 offset:512
.LBB0_2296:
	s_or_b64 exec, exec, s[60:61]
	s_waitcnt vmcnt(13) lgkmcnt(0)
	v_lshlrev_b32_e32 v94, 16, v148
	v_and_b32_e32 v95, 0xffff0000, v148
	v_pk_add_f32 v[90:91], v[90:91], v[94:95]
	v_lshlrev_b32_e32 v94, 16, v149
	v_and_b32_e32 v95, 0xffff0000, v149
	v_pk_add_f32 v[94:95], v[92:93], v[94:95]
	v_pk_mul_f32 v[148:149], v[90:91], v[90:91]
	v_pk_mul_f32 v[150:151], v[94:95], v[94:95]
	s_waitcnt vmcnt(12)
	v_lshlrev_b32_e32 v92, 16, v146
	v_and_b32_e32 v93, 0xffff0000, v146
	v_add_f32_e32 v0, v148, v149
	v_pk_add_f32 v[92:93], v[86:87], v[92:93]
	v_lshlrev_b32_e32 v86, 16, v147
	v_and_b32_e32 v87, 0xffff0000, v147
	v_add_f32_e32 v0, v150, v0
	v_pk_add_f32 v[88:89], v[88:89], v[86:87]
	v_pk_mul_f32 v[86:87], v[92:93], v[92:93]
	v_add_f32_e32 v0, v151, v0
	v_add_f32_e32 v0, v86, v0
	v_pk_mul_f32 v[146:147], v[88:89], v[88:89]
	v_add_f32_e32 v0, v87, v0
	v_add_f32_e32 v0, v146, v0
	v_add_f32_e32 v0, v147, v0
	v_mov_b32_e32 v86, v0
	s_nop 1
	v_permlane16_swap_b32_e32 v86, v0
	s_waitcnt lgkmcnt(0)
	v_add_f32_e32 v0, v0, v86
	v_mov_b32_e32 v86, v0
	s_nop 1
	v_permlane32_swap_b32_e32 v86, v0
	s_and_saveexec_b64 s[60:61], s[4:5]
	s_cbranch_execz .LBB0_2298
	s_waitcnt lgkmcnt(0)
	v_add_f32_e32 v0, v0, v86
	ds_write_b32 v189, v0 offset:1024
.LBB0_2298:
	s_or_b64 exec, exec, s[60:61]
	s_waitcnt vmcnt(11) lgkmcnt(0)
	v_lshlrev_b32_e32 v86, 16, v142
	v_and_b32_e32 v87, 0xffff0000, v142
	v_pk_add_f32 v[86:87], v[82:83], v[86:87]
	v_lshlrev_b32_e32 v82, 16, v143
	v_and_b32_e32 v83, 0xffff0000, v143
	v_pk_add_f32 v[84:85], v[84:85], v[82:83]
	v_pk_mul_f32 v[142:143], v[86:87], v[86:87]
	v_pk_mul_f32 v[146:147], v[84:85], v[84:85]
	s_waitcnt vmcnt(10)
	v_lshlrev_b32_e32 v82, 16, v140
	v_and_b32_e32 v83, 0xffff0000, v140
	v_add_f32_e32 v0, v142, v143
	v_pk_add_f32 v[82:83], v[78:79], v[82:83]
	v_lshlrev_b32_e32 v78, 16, v141
	v_and_b32_e32 v79, 0xffff0000, v141
	v_add_f32_e32 v0, v146, v0
	v_pk_add_f32 v[78:79], v[80:81], v[78:79]
	v_pk_mul_f32 v[80:81], v[82:83], v[82:83]
	v_add_f32_e32 v0, v147, v0
	v_add_f32_e32 v0, v80, v0
	v_pk_mul_f32 v[140:141], v[78:79], v[78:79]
	v_add_f32_e32 v0, v81, v0
	v_add_f32_e32 v0, v140, v0
	v_add_f32_e32 v0, v141, v0
	v_mov_b32_e32 v80, v0
	s_nop 1
	v_permlane16_swap_b32_e32 v80, v0
	s_waitcnt lgkmcnt(0)
	v_add_f32_e32 v0, v0, v80
	v_mov_b32_e32 v80, v0
	s_nop 1
	v_permlane32_swap_b32_e32 v80, v0
	s_and_saveexec_b64 s[60:61], s[4:5]
	s_cbranch_execz .LBB0_2282
	s_waitcnt lgkmcnt(0)
	v_add_f32_e32 v0, v0, v80
	ds_write_b32 v189, v0 offset:1536
	s_branch .LBB0_2282
